# plus init_rows modulate step: modulation-vector groups 2-4 of a row requested right after group 1 into dead registers
# baseline (speedup 1.0000x reference)
; __device__ __forceinline__ unsigned pk2(float lo, float hi) { unsigned r; asm("v_cvt_pk_bf16_f32 %0, %1, %2" : "=v"(r) : "v"(lo), "v"(hi)); return r; }
; __device__ __forceinline__ void init_rows(const Params& P) {
;     ...
;     for (int r = gw; r < M; r += NGW) {
;         const int b = r / TPB, p = r - b * TPB; const bool isctx = p < CTX;
;         f32x4 nv[8];
; #pragma unroll
;         for (int j = 0; j < 8; ++j) nv[j] = (f32x4){0.f, 0.f, 0.f, 0.f};
;         if (r + NGW < M) { const float* s1 = INIT_SRC(r + NGW);
; #pragma unroll
;             for (int j = 0; j < 8; ++j) nv[j] = __builtin_nontemporal_load((const f32x4*)(s1 + ((j >> 1) * 64 + lane) * 8 + (j & 1) * 4)); }
;         const float* mv = mod + (size_t)(isctx ? 2 : b) * (6 * D);
; #pragma unroll
;         for (int jj = 0; jj < 4; ++jj) { const int c = (jj * 64 + lane) * 8; const f32x4 v0 = cv[2 * jj], v1 = cv[2 * jj + 1];
;             *(f32x4*)(X + (size_t)r * D + c) = v0; *(f32x4*)(X + (size_t)r * D + c + 4) = v1;
;             const f32x4 y0 = v0 * (1.f + *(const f32x4*)(mv + D + c)) + *(const f32x4*)(mv + c), y1 = v1 * (1.f + *(const f32x4*)(mv + D + c + 4)) + *(const f32x4*)(mv + c + 4);
;             u32x4 o; o.x = pk2(y0[0], y0[1]); o.y = pk2(y0[2], y0[3]); o.z = pk2(y1[0], y1[1]); o.w = pk2(y1[2], y1[3]); *(u32x4*)(U + (size_t)r * D + c) = o; }
; #pragma unroll
;         for (int j = 0; j < 8; ++j) cv[j] = nv[j];
;     }
.LBB0_113:
	s_or_b64 exec, exec, s[14:15]
	v_mul_hi_i32 v69, v74, s17
	v_lshrrev_b32_e32 v71, 31, v69
	v_ashrrev_i32_e32 v69, 11, v69
	v_add_u32_e32 v69, v69, v71
	v_mad_i32_i24 v71, v69, s21, v74
	v_cmp_lt_i32_e64 s[0:1], s22, v71
	v_ashrrev_i32_e32 v75, 31, v74
	v_mov_b32_e32 v71, v65
	v_cndmask_b32_e64 v69, 2, v69, s[0:1]
	v_readlane_b32 s0, v252, 6
	v_mul_hi_i32_i24_e32 v77, 0xc000, v69
	v_mul_i32_i24_e32 v76, 0xc000, v69
	v_readlane_b32 s1, v252, 7
	v_mov_b32_e32 v69, v65
	v_mov_b32_e32 v73, v65
	v_lshl_add_u64 v[78:79], s[0:1], 0, v[76:77]
	v_lshlrev_b64 v[76:77], 13, v[74:75]
	v_lshl_add_u64 v[98:99], s[26:27], 0, v[76:77]
	v_lshl_add_u64 v[100:101], v[78:79], 0, s[12:13]
	v_lshl_add_u64 v[102:103], v[98:99], 0, v[64:65]
	s_waitcnt vmcnt(7)
	global_store_dwordx4 v[102:103], v[24:27], off
	s_waitcnt vmcnt(7)
	global_store_dwordx4 v[102:103], v[28:31], off offset:16
	v_lshl_add_u64 v[76:77], v[100:101], 0, v[64:65]
	global_load_dwordx4 v[82:85], v[76:77], off
	global_load_dwordx4 v[86:89], v[76:77], off offset:16
	v_lshl_add_u64 v[104:105], v[78:79], 0, v[64:65]
	global_load_dwordx4 v[90:93], v[104:105], off
	global_load_dwordx4 v[94:97], v[104:105], off offset:16
	v_lshl_add_u64 v[106:107], v[100:101], 0, v[68:69]
	global_load_dwordx4 v[110:113], v[106:107], off offset:16
	global_load_dwordx4 v[106:109], v[106:107], off
	global_load_dwordx4 v[114:117], v[104:105], off offset:2048
	global_load_dwordx4 v[118:121], v[104:105], off offset:2064
	v_lshl_add_u64 v[122:123], v[100:101], 0, v[70:71]
	global_load_dwordx4 v[126:129], v[122:123], off offset:16
	global_load_dwordx4 v[122:125], v[122:123], off
	v_lshl_add_u64 v[130:131], v[78:79], 0, v[70:71]
	global_load_dwordx4 v[134:137], v[130:131], off offset:16
	global_load_dwordx4 v[130:133], v[130:131], off
	v_lshl_add_u64 v[138:139], v[100:101], 0, v[72:73]
	global_load_dwordx4 v[142:145], v[138:139], off offset:16
	global_load_dwordx4 v[138:141], v[138:139], off
	v_lshl_add_u64 v[146:147], v[78:79], 0, v[72:73]
	global_load_dwordx4 v[150:153], v[146:147], off offset:16
	global_load_dwordx4 v[146:149], v[146:147], off
	v_lshlrev_b64 v[74:75], 12, v[74:75]
	v_lshl_add_u64 v[76:77], v[66:67], 0, v[74:75]
	v_lshl_add_u64 v[74:75], v[100:101], 0, v[68:69]
	s_and_b64 s[0:1], exec, vcc
	s_or_b64 s[10:11], s[0:1], s[10:11]
	s_waitcnt vmcnt(15)
	v_pk_add_f32 v[84:85], v[84:85], 1.0 op_sel_hi:[1,0]
	v_pk_add_f32 v[82:83], v[82:83], 1.0 op_sel_hi:[1,0]
	s_waitcnt vmcnt(14)
	v_pk_add_f32 v[88:89], v[88:89], 1.0 op_sel_hi:[1,0]
	v_pk_add_f32 v[86:87], v[86:87], 1.0 op_sel_hi:[1,0]
	s_waitcnt vmcnt(13)
	v_pk_fma_f32 v[26:27], v[26:27], v[84:85], v[92:93]
	v_pk_fma_f32 v[24:25], v[24:25], v[82:83], v[90:91]
	s_waitcnt vmcnt(12)
	v_pk_fma_f32 v[30:31], v[30:31], v[88:89], v[96:97]
	v_pk_fma_f32 v[28:29], v[28:29], v[86:87], v[94:95]
	v_cvt_pk_bf16_f32 v24, v24, v25
	v_cvt_pk_bf16_f32 v25, v26, v27
	v_cvt_pk_bf16_f32 v27, v30, v31
	v_lshl_add_u64 v[90:91], v[100:101], 0, v[70:71]
	v_cvt_pk_bf16_f32 v26, v28, v29
	global_store_dwordx4 v[76:77], v[24:27], off
	global_store_dwordx4 v[102:103], v[16:19], off offset:2048
	global_store_dwordx4 v[102:103], v[20:23], off offset:2064
	s_nop 0
	v_lshl_add_u64 v[74:75], v[98:99], 0, v[70:71]
	s_waitcnt vmcnt(11)
	v_pk_add_f32 v[26:27], v[108:109], 1.0 op_sel_hi:[1,0]
	v_pk_add_f32 v[24:25], v[106:107], 1.0 op_sel_hi:[1,0]
	v_pk_add_f32 v[30:31], v[112:113], 1.0 op_sel_hi:[1,0]
	v_pk_add_f32 v[28:29], v[110:111], 1.0 op_sel_hi:[1,0]
	v_pk_fma_f32 v[18:19], v[18:19], v[26:27], v[116:117]
	v_pk_fma_f32 v[16:17], v[16:17], v[24:25], v[114:115]
	v_pk_fma_f32 v[22:23], v[22:23], v[30:31], v[120:121]
	v_pk_fma_f32 v[20:21], v[20:21], v[28:29], v[118:119]
	v_cvt_pk_bf16_f32 v16, v16, v17
	v_cvt_pk_bf16_f32 v17, v18, v19
	v_cvt_pk_bf16_f32 v19, v22, v23
	v_lshl_add_u64 v[28:29], v[78:79], 0, v[70:71]
	v_cvt_pk_bf16_f32 v18, v20, v21
	global_store_dwordx4 v[76:77], v[16:19], off offset:1024
	global_store_dwordx4 v[74:75], v[8:11], off
	global_store_dwordx4 v[74:75], v[12:15], off offset:16
	s_nop 0
	s_nop 0
	v_lshl_add_u64 v[74:75], v[98:99], 0, v[72:73]
	v_lshl_add_u64 v[86:87], v[100:101], 0, v[72:73]
	s_waitcnt vmcnt(10)
	v_pk_add_f32 v[18:19], v[124:125], 1.0 op_sel_hi:[1,0]
	v_pk_add_f32 v[16:17], v[122:123], 1.0 op_sel_hi:[1,0]
	v_pk_add_f32 v[22:23], v[128:129], 1.0 op_sel_hi:[1,0]
	v_pk_add_f32 v[20:21], v[126:127], 1.0 op_sel_hi:[1,0]
	v_pk_fma_f32 v[10:11], v[10:11], v[18:19], v[132:133]
	v_pk_fma_f32 v[8:9], v[8:9], v[16:17], v[130:131]
	v_pk_fma_f32 v[14:15], v[14:15], v[22:23], v[136:137]
	v_pk_fma_f32 v[12:13], v[12:13], v[20:21], v[134:135]
	v_cvt_pk_bf16_f32 v8, v8, v9
	v_cvt_pk_bf16_f32 v9, v10, v11
	v_cvt_pk_bf16_f32 v11, v14, v15
	v_mov_b32_e32 v20, v40
	v_cvt_pk_bf16_f32 v10, v12, v13
	global_store_dwordx4 v[76:77], v[8:11], off offset:2048
	global_store_dwordx4 v[74:75], v[0:3], off
	global_store_dwordx4 v[74:75], v[4:7], off offset:16
	s_nop 0
	v_lshl_add_u64 v[8:9], v[78:79], 0, v[72:73]
	v_mov_b32_e32 v21, v41
	v_mov_b32_e32 v22, v42
	v_mov_b32_e32 v23, v43
	v_mov_b32_e32 v12, v44
	v_mov_b32_e32 v13, v45
	v_mov_b32_e32 v14, v46
	v_mov_b32_e32 v15, v47
	v_mov_b32_e32 v74, v80
	v_mov_b32_e32 v24, v60
	v_mov_b32_e32 v25, v61
	v_mov_b32_e32 v26, v62
	v_mov_b32_e32 v27, v63
	v_mov_b32_e32 v28, v48
	v_mov_b32_e32 v29, v49
	v_mov_b32_e32 v30, v50
	v_mov_b32_e32 v31, v51
	v_mov_b32_e32 v16, v56
	v_mov_b32_e32 v17, v57
	v_mov_b32_e32 v18, v58
	v_mov_b32_e32 v19, v59
	v_mov_b32_e32 v8, v52
	v_mov_b32_e32 v9, v53
	v_mov_b32_e32 v10, v54
	v_mov_b32_e32 v11, v55
	s_waitcnt vmcnt(9)
	v_pk_add_f32 v[40:41], v[140:141], 1.0 op_sel_hi:[1,0]
	v_pk_add_f32 v[42:43], v[138:139], 1.0 op_sel_hi:[1,0]
	v_pk_add_f32 v[44:45], v[144:145], 1.0 op_sel_hi:[1,0]
	v_pk_add_f32 v[46:47], v[142:143], 1.0 op_sel_hi:[1,0]
	v_pk_fma_f32 v[40:41], v[2:3], v[40:41], v[148:149]
	v_pk_fma_f32 v[42:43], v[0:1], v[42:43], v[146:147]
	v_pk_fma_f32 v[44:45], v[6:7], v[44:45], v[152:153]
	v_pk_fma_f32 v[46:47], v[4:5], v[46:47], v[150:151]
	v_mov_b32_e32 v0, v36
	v_mov_b32_e32 v1, v37
	v_mov_b32_e32 v2, v38
	v_mov_b32_e32 v3, v39
	v_mov_b32_e32 v4, v32
	v_mov_b32_e32 v5, v33
	v_mov_b32_e32 v6, v34
	v_mov_b32_e32 v7, v35
	v_cvt_pk_bf16_f32 v36, v42, v43
	v_cvt_pk_bf16_f32 v37, v40, v41
	v_cvt_pk_bf16_f32 v38, v46, v47
	v_cvt_pk_bf16_f32 v39, v44, v45
	global_store_dwordx4 v[76:77], v[36:39], off offset:3072
	s_andn2_b64 exec, exec, s[10:11]
	s_cbranch_execz .LBB0_116
